# S5-Y: vblock-local 4-wave LDS-counter barrier instead of workgroup s_barrier in the tile loop, second vblock takes t-blocks in a shifted order
# speedup vs baseline: 1.0014x; 1.0014x over previous
; #define VBID ((int)(blockIdx.x * 2 + (otid() >> 8)))
; DI void phase_s5_y(const Params& p, char* lds) {
;   const bf16_t* ugm = (const bf16_t*)(p.ws + W_SLOT1);
;   const bf16_t* H = (const bf16_t*)(p.ws + W_H);
;   const bf16_t* MC = (const bf16_t*)(p.ws + W_MC);
;   const bf16_t* KT = (const bf16_t*)(p.ws + W_KTAB);
;   bf16_t* yg = (bf16_t*)(p.ws + W_SLOT3);
;   const bf16_t* zblk = (const bf16_t*)(p.ws + W_ZERO);
;   const int nt = 64 * 8 * 8;
;   for (int k_ = 0; k_ * VGRID < (nt); ++k_) {
;     int L = k_ * VGRID + VBID; const bool active_ = L < (nt); if (!active_) L = (nt) - 1;
;     const int j = 3 - (L >> 10), rem = L & 1023, g = rem >> 4, mt = rem & 15;
.LBB0_623:
	s_or_b64 exec, exec, s[4:5]
	s_mov_b32 s1, 0
	s_waitcnt lgkmcnt(0)
	s_barrier
	s_ashr_i32 s3, s1, 31
	v_readlane_b32 s4, v251, 3
	v_readlane_b32 s5, v251, 4
	s_add_u32 s2, s4, s1
	s_addc_u32 s3, s5, s3
	s_load_dwordx2 s[4:5], s[2:3], 0x98
	s_load_dwordx2 s[16:17], s[2:3], 0xf8
	v_mov_b32_e32 v0, v182
	s_mov_b32 s0, 0
	v_lshlrev_b32_e32 v0, 8, v0
	s_waitcnt lgkmcnt(0)
	s_add_u32 s6, s16, 0x9880000
	s_addc_u32 s7, s17, 0
	s_add_u32 s8, s16, 0x27c00000
	s_addc_u32 s9, s17, 0
	s_add_u32 s10, s16, 0x22c00000
	s_addc_u32 s11, s17, 0
	s_add_u32 s12, s16, 0x21a00000
	s_addc_u32 s13, s17, 0
	s_add_u32 s14, s16, 0x19980000
	s_addc_u32 s15, s17, 0
	s_add_u32 s30, s16, 0x16a4000
	v_and_b32_e32 v102, 0xffff0000, v0
	s_addc_u32 s31, s17, 0
	v_mov_b32_e32 v69, 0
	s_movk_i32 s33, 0x100
	s_movk_i32 s34, 0x200
	s_movk_i32 s35, 0x300
	s_mov_b64 s[16:17], 0x80
	s_mov_b64 s[18:19], 0x4000
	s_mov_b64 s[20:21], 0x8000
	s_mov_b64 s[22:23], 0xc000
	s_mov_b64 s[24:25], 0x100000
	s_mov_b64 s[26:27], 0x200000
	s_mov_b64 s[28:29], 0x300000
	v_mov_b32_e32 v103, 4
	s_mov_b32 s36, 0
	v_lshrrev_b32_e32 v168, 8, v182
	v_lshlrev_b32_e32 v168, 8, v168
	v_add_u32_e32 v168, 0x20000, v168
	v_mov_b32_e32 v169, 0
	ds_write_b32 v168, v169
	v_mov_b32_e32 v169, 1
	s_mov_b32 s66, 0
	s_waitcnt lgkmcnt(0)
	s_barrier
	s_branch .LBB0_625

; #define VBID ((int)(blockIdx.x * 2 + (otid() >> 8)))
; #define LAS __attribute__((address_space(3)))
; template <class FA, class FB, class FL, class FS>
; DI void gemm_tile(char* lds, int ksteps, int rot, FA fa, FB fb, FL fl, FS fs) {
;     ...
; #pragma unroll
;   for (int i = 0; i < 4; ++i) {
;     const int id = tid + i * 256, r = id >> 3, c = (id & 7) ^ (r & 7);
;     __builtin_amdgcn_global_load_lds((const unsigned*)fa(r, rot * 8 + c), (LAS unsigned*)(l3 + id * 16), 16, 0, 0);
;     __builtin_amdgcn_global_load_lds((const unsigned*)fb(r, rot * 8 + c), (LAS unsigned*)(l3 + 16384 + id * 16), 16, 0, 0);
;   }
;   asm volatile("s_waitcnt vmcnt(0)" ::: "memory");
;   __syncthreads();
; DI void phase_s5_y(const Params& p, char* lds) {
;     ...
;   for (int k_ = 0; k_ * VGRID < (nt); ++k_) {
;     int L = k_ * VGRID + VBID; const bool active_ = L < (nt); if (!active_) L = (nt) - 1;
;     const int j = 3 - (L >> 10), rem = L & 1023, g = rem >> 4, mt = rem & 15;
;     const bf16_t* Ug = ugm + (size_t)g * MP * 16 + (size_t)mt * 128 * 512;
;     const bf16_t* Hg = H + ((size_t)g * 2048 + mt * 128) * 128;
;     gemm_tile(lds, 2 + 2 * (j + 1), 0,
.LBB0_625:
	v_mov_b32_e32 v0, v182
	v_readlane_b32 s1, v251, 7
	v_ashrrev_i32_e32 v0, 8, v0
	s_add_i32 s0, s0, s1
	v_add_u32_e32 v0, s0, v0
	v_min_i32_e32 v0, 0xfff, v0
	v_and_b32_e32 v70, 0x600, v0
	v_and_b32_e32 v71, 0x800, v0
	v_and_b32_e32 v0, 0x1ff, v0
	v_lshl_or_b32 v0, v70, 1, v0
	v_lshrrev_b32_e32 v71, 2, v71
	v_or_b32_e32 v0, v0, v71
	v_and_b32_e32 v70, 1, v0
	v_lshlrev_b32_e32 v70, 11, v70
	v_xor_b32_e32 v0, v0, v70
	v_bfe_u32 v70, v0, 4, 6
	v_and_b32_e32 v71, 15, v0
	v_lshlrev_b32_e32 v68, 19, v70
	v_mov_b32_e32 v26, v182
	v_ashrrev_i32_e32 v154, 10, v0
	v_lshl_add_u64 v[0:1], s[8:9], 0, v[68:69]
	v_lshlrev_b32_e32 v68, 15, v71
	v_lshl_add_u64 v[6:7], v[0:1], 0, v[68:69]
	v_bfe_u32 v24, v26, 3, 5
	v_xor_b32_e32 v0, v24, v26
	v_lshlrev_b32_sdwa v82, v103, v26 dst_sel:DWORD dst_unused:UNUSED_PAD src0_sel:DWORD src1_sel:BYTE_0
	v_lshlrev_b32_e32 v68, 8, v24
	v_lshlrev_b32_e32 v0, 4, v0
	v_add_u32_e32 v56, v102, v82
	v_sub_u32_e32 v91, 3, v154
	v_lshl_add_u64 v[8:9], v[6:7], 0, v[68:69]
	v_and_b32_e32 v68, 0x70, v0
	v_readfirstlane_b32 s0, v56
	v_lshl_add_u64 v[0:1], v[8:9], 0, v[68:69]
	s_mov_b32 m0, s0
	v_lshlrev_b32_e32 v81, 7, v91
	global_load_lds_dwordx4 v[0:1], off
	v_or_b32_e32 v0, v81, v24
	v_mov_b32_e32 v1, v69
	v_lshlrev_b32_e32 v2, 17, v70
	v_mov_b32_e32 v3, v69
	v_lshl_add_u64 v[10:11], s[10:11], 0, v[2:3]
	v_lshlrev_b64 v[2:3], 8, v[0:1]
	v_add_u32_e32 v1, 0x4000, v56
	v_lshl_add_u64 v[22:23], v[10:11], 0, v[2:3]
	v_readfirstlane_b32 s0, v1
	v_or_b32_sdwa v1, v26, s33 dst_sel:DWORD dst_unused:UNUSED_PAD src0_sel:BYTE_0 src1_sel:DWORD
	v_lshl_add_u64 v[2:3], v[22:23], 0, v[68:69]
	s_mov_b32 m0, s0
	v_lshrrev_b32_e32 v155, 3, v1
	global_load_lds_dwordx4 v[2:3], off
	v_xor_b32_e32 v2, v155, v26
	v_lshlrev_b32_e32 v83, 4, v1
	v_lshlrev_b32_e32 v68, 8, v155
	v_lshlrev_b32_e32 v2, 4, v2
	v_add_u32_e32 v1, v102, v83
	v_lshl_add_u64 v[60:61], v[6:7], 0, v[68:69]
	v_and_b32_e32 v68, 0x70, v2
	v_readfirstlane_b32 s0, v1
	v_lshl_add_u64 v[2:3], v[60:61], 0, v[68:69]
	s_mov_b32 m0, s0
	v_lshrrev_b32_e32 v80, 4, v26
	global_load_lds_dwordx4 v[2:3], off
	v_or_b32_e32 v2, v81, v155
	v_mov_b32_e32 v3, v69
	v_lshlrev_b64 v[4:5], 8, v[2:3]
	v_add_u32_e32 v3, 0x4000, v1
	v_lshl_add_u64 v[62:63], v[10:11], 0, v[4:5]
	v_readfirstlane_b32 s0, v3
	v_or_b32_sdwa v3, v26, s34 dst_sel:DWORD dst_unused:UNUSED_PAD src0_sel:BYTE_0 src1_sel:DWORD
	v_lshl_add_u64 v[4:5], v[62:63], 0, v[68:69]
	s_mov_b32 m0, s0
	v_lshrrev_b32_e32 v156, 3, v3
	global_load_lds_dwordx4 v[4:5], off
	v_xor_b32_e32 v4, v156, v26
	v_lshlrev_b32_e32 v84, 4, v3
	v_lshlrev_b32_e32 v68, 8, v156
	v_lshlrev_b32_e32 v4, 4, v4
	v_add_u32_e32 v3, v102, v84
	v_lshl_add_u64 v[64:65], v[6:7], 0, v[68:69]
	v_and_b32_e32 v68, 0x70, v4
	v_readfirstlane_b32 s0, v3
	v_lshl_add_u64 v[4:5], v[64:65], 0, v[68:69]
	s_mov_b32 m0, s0
	v_and_b32_e32 v25, 7, v26
	global_load_lds_dwordx4 v[4:5], off
	v_or_b32_e32 v4, v81, v156
	v_mov_b32_e32 v5, v69
	v_lshlrev_b64 v[12:13], 8, v[4:5]
	v_add_u32_e32 v5, 0x4000, v3
	v_lshl_add_u64 v[76:77], v[10:11], 0, v[12:13]
	v_readfirstlane_b32 s0, v5
	v_or_b32_sdwa v5, v26, s35 dst_sel:DWORD dst_unused:UNUSED_PAD src0_sel:BYTE_0 src1_sel:DWORD
	v_lshl_add_u64 v[12:13], v[76:77], 0, v[68:69]
	s_mov_b32 m0, s0
	v_lshrrev_b32_e32 v157, 3, v5
	global_load_lds_dwordx4 v[12:13], off
	v_xor_b32_e32 v12, v157, v26
	v_lshlrev_b32_e32 v68, 8, v157
	v_lshlrev_b32_e32 v85, 4, v5
	v_lshl_add_u64 v[100:101], v[6:7], 0, v[68:69]
	v_lshlrev_b32_e32 v6, 4, v12
	v_add_u32_e32 v5, v102, v85
	v_and_b32_e32 v68, 0x70, v6
	v_readfirstlane_b32 s0, v5
	v_lshl_add_u64 v[6:7], v[100:101], 0, v[68:69]
	s_mov_b32 m0, s0
	v_and_b32_e32 v79, 15, v26
	global_load_lds_dwordx4 v[6:7], off
	v_or_b32_e32 v6, v81, v157
	v_mov_b32_e32 v7, v69
	v_lshlrev_b64 v[12:13], 8, v[6:7]
	v_add_u32_e32 v7, 0x4000, v5
	v_lshl_add_u64 v[148:149], v[10:11], 0, v[12:13]
	v_readfirstlane_b32 s0, v7
	v_lshl_add_u64 v[10:11], v[148:149], 0, v[68:69]
	s_mov_b32 m0, s0
	v_lshlrev_b32_e32 v68, 21, v70
	global_load_lds_dwordx4 v[10:11], off
	v_lshl_add_u64 v[10:11], s[6:7], 0, v[68:69]
	v_lshlrev_b32_e32 v68, 17, v71
	v_bfe_u32 v7, v26, 4, 2
	v_lshl_add_u64 v[152:153], v[10:11], 0, v[68:69]
	v_bitop3_b32 v10, v80, v25, 3 bitop3:0x6c
	v_bitop3_b32 v7, v7, v25, 4 bitop3:0x36
	v_bfe_u32 v78, v26, 6, 1
	v_bfe_u32 v86, v26, 7, 1
	v_lshlrev_b32_e32 v87, 4, v10
	v_lshlrev_b32_e32 v14, 7, v79
	v_lshlrev_b32_e32 v90, 4, v7
	v_lshlrev_b32_e32 v7, 7, v26
	v_lshl_or_b32 v88, v78, 13, v14
	v_add_u32_e32 v15, v102, v87
	v_lshl_or_b32 v89, v86, 13, v14
	v_lshlrev_b32_e32 v68, 10, v24
	v_and_b32_e32 v7, 0x3c00, v7
	v_bitop3_b32 v158, v24, 7, v26 bitop3:0x48
	v_add_u32_e32 v27, v15, v88
	v_add_u32_e32 v57, v15, v89
	v_lshl_add_u64 v[24:25], v[152:153], 0, v[68:69]
	v_lshl_or_b32 v68, v70, 14, v7
	s_waitcnt vmcnt(0)
	s_waitcnt vmcnt(0) lgkmcnt(0)
	s_add_i32 s66, s66, 4
	s_mov_b64 s[68:69], exec
	s_mov_b64 exec, 1
	s_nop 1
	ds_add_u32 v168, v169
	s_movk_i32 s67, 0x800
; #define MFMA16(a, b, c) __builtin_amdgcn_mfma_f32_16x16x32_bf16((a), (b), (c), 0, 0, 0)
; #define LAS __attribute__((address_space(3)))
; template <class FA, class FB, class FL, class FS>
; DI void gemm_tile(char* lds, int ksteps, int rot, FA fa, FB fb, FL fl, FS fs) {
;     ...
;   for (int ks = 0; ks < ksteps; ++ks) {
;     const int cur = ks & 1;
;     if (ks + 1 < ksteps) {
;       int kn = ks + 1 + rot; if (kn >= ksteps) kn -= ksteps;
;       LAS char* dst = l3 + (cur ^ 1) * 32768;
; #pragma unroll
;       for (int i = 0; i < 4; ++i) {
;         const int id = tid + i * 256, r = id >> 3, c = (id & 7) ^ (r & 7);
;         __builtin_amdgcn_global_load_lds((const unsigned*)fa(r, kn * 8 + c), (LAS unsigned*)(dst + id * 16), 16, 0, 0);
;         __builtin_amdgcn_global_load_lds((const unsigned*)fb(r, kn * 8 + c), (LAS unsigned*)(dst + 16384 + id * 16), 16, 0, 0);
;       }
;     }
;     const char* A = lds + cur * 32768;
;     const char* B = A + 16384;
; #pragma unroll
;     for (int kk = 0; kk < 2; ++kk) {
;       bf16x8 af[4], bq[4];
; #pragma unroll
;       for (int m = 0; m < 4; ++m) af[m] = ldfrag(A, 128, wr * 64 + m * 16 + fr, kk * 4 + fq);
; #pragma unroll
;       for (int n = 0; n < 4; ++n) bq[n] = ldfrag(B, 128, wc * 64 + n * 16 + fr, kk * 4 + fq);
; #pragma unroll
;       for (int m = 0; m < 4; ++m)
; #pragma unroll
;         for (int n = 0; n < 4; ++n) acc[m][n] = MFMA16(bq[n], af[m], acc[m][n]);
.Ls5sb_spin0:
	ds_read_b32 v170, v168
	s_waitcnt lgkmcnt(0)
	v_readfirstlane_b32 s70, v170
	s_sub_i32 s67, s67, 1
	s_cmp_ge_u32 s70, s66
	s_cbranch_scc1 .Ls5sb_done0
	s_cmp_gt_i32 s67, 0
	s_cbranch_scc1 .Ls5sb_spin0
.Ls5sb_done0:
	s_mov_b64 exec, s[68:69]
	s_nop 1
	ds_read_b128 v[10:13], v27 offset:16384
	ds_read_b128 v[14:17], v57
	ds_read_b128 v[18:21], v27 offset:18432
	v_bitop3_b32 v159, v155, 7, v26 bitop3:0x48
	ds_read_b128 v[28:31], v57 offset:2048
	ds_read_b128 v[32:35], v27 offset:20480
	v_bitop3_b32 v160, v156, 7, v26 bitop3:0x48
	v_bitop3_b32 v161, v157, 7, v26 bitop3:0x48
	ds_read_b128 v[40:43], v27 offset:22528
	v_lshl_add_u64 v[26:27], s[12:13], 0, v[68:69]
	v_lshlrev_b32_e32 v68, 4, v158
	v_add_u32_e32 v7, 0x8000, v56
	v_lshl_add_u64 v[8:9], v[8:9], 0, v[68:69]
	v_readfirstlane_b32 s0, v7
	v_lshl_add_u64 v[8:9], v[8:9], 0, s[16:17]
	s_mov_b32 m0, s0
	v_add_u32_e32 v7, 0xc000, v56
	global_load_lds_dwordx4 v[8:9], off
	v_lshl_add_u64 v[8:9], v[22:23], 0, v[68:69]
	v_readfirstlane_b32 s0, v7
	v_add_u32_e32 v7, 0x8000, v1
	v_lshl_add_u64 v[8:9], v[8:9], 0, s[16:17]
	s_mov_b32 m0, s0
	v_readfirstlane_b32 s0, v7
	v_add_u32_e32 v1, 0xc000, v1
	global_load_lds_dwordx4 v[8:9], off
	s_mov_b32 m0, s0
	v_readfirstlane_b32 s0, v1
	v_add_u32_e32 v1, v102, v90
	v_lshlrev_b32_e32 v68, 4, v159
	v_add_u32_e32 v7, v1, v88
	ds_read_b128 v[52:55], v57 offset:4096
	ds_read_b128 v[124:127], v7 offset:16384
	ds_read_b128 v[56:59], v57 offset:6144
	v_lshl_add_u64 v[8:9], v[60:61], 0, v[68:69]
	v_lshl_add_u64 v[8:9], v[8:9], 0, s[16:17]
	global_load_lds_dwordx4 v[8:9], off
	v_lshl_add_u64 v[8:9], v[62:63], 0, v[68:69]
	v_lshl_add_u64 v[22:23], v[8:9], 0, s[16:17]
	s_mov_b32 m0, s0
	v_add_u32_e32 v1, v1, v89
	global_load_lds_dwordx4 v[22:23], off
	s_waitcnt lgkmcnt(0)
	v_mfma_f32_16x16x32_bf16 v[44:47], v[18:21], v[14:17], 0
	v_lshlrev_b32_e32 v68, 4, v160
	v_add_u32_e32 v22, 0x8000, v3
	v_add_u32_e32 v3, 0xc000, v3
	v_mfma_f32_16x16x32_bf16 v[48:51], v[32:35], v[14:17], 0
	v_readfirstlane_b32 s0, v22
	s_mov_b32 m0, s0
	v_readfirstlane_b32 s0, v3
	v_mfma_f32_16x16x32_bf16 v[92:95], v[18:21], v[28:31], 0
	v_add_u32_e32 v3, 0x8000, v5
	v_lshl_add_u32 v91, v91, 1, 4
	s_mov_b32 s37, -9
	v_mfma_f32_16x16x32_bf16 v[96:99], v[32:35], v[28:31], 0
	s_mov_b32 s38, 0
	s_mov_b32 s39, 0x8000
	v_mfma_f32_16x16x32_bf16 v[108:111], v[18:21], v[52:55], 0
	v_mfma_f32_16x16x32_bf16 v[112:115], v[32:35], v[52:55], 0
	v_mfma_f32_16x16x32_bf16 v[120:123], v[18:21], v[56:59], 0
	ds_read_b128 v[18:21], v1
	ds_read_b128 v[132:135], v7 offset:18432
	v_mfma_f32_16x16x32_bf16 v[128:131], v[32:35], v[56:59], 0
	ds_read_b128 v[32:35], v1 offset:2048
	ds_read_b128 v[140:143], v7 offset:20480
	ds_read_b128 v[144:147], v7 offset:22528
	v_mfma_f32_16x16x32_bf16 v[36:39], v[10:13], v[14:17], 0
	v_mfma_f32_16x16x32_bf16 v[72:75], v[10:13], v[28:31], 0
	v_mfma_f32_16x16x32_bf16 v[104:107], v[10:13], v[52:55], 0
	v_mfma_f32_16x16x32_bf16 v[8:11], v[10:13], v[56:59], 0
	v_lshl_add_u64 v[12:13], v[64:65], 0, v[68:69]
	v_lshl_add_u64 v[12:13], v[12:13], 0, s[16:17]
	global_load_lds_dwordx4 v[12:13], off
	v_lshl_add_u64 v[12:13], v[76:77], 0, v[68:69]
	v_mfma_f32_16x16x32_bf16 v[14:17], v[40:43], v[14:17], 0
	v_lshl_add_u64 v[12:13], v[12:13], 0, s[16:17]
	s_mov_b32 m0, s0
	v_lshlrev_b32_e32 v68, 4, v161
	global_load_lds_dwordx4 v[12:13], off
	v_lshl_add_u64 v[12:13], v[100:101], 0, v[68:69]
	v_readfirstlane_b32 s0, v3
	v_lshl_add_u64 v[12:13], v[12:13], 0, s[16:17]
	s_mov_b32 m0, s0
	v_add_u32_e32 v3, 0xc000, v5
	global_load_lds_dwordx4 v[12:13], off
	v_lshl_add_u64 v[12:13], v[148:149], 0, v[68:69]
	v_readfirstlane_b32 s0, v3
	v_mfma_f32_16x16x32_bf16 v[116:119], v[40:43], v[52:55], 0
	s_mov_b32 m0, s0
	ds_read_b128 v[148:151], v1 offset:6144
	v_lshlrev_b32_e32 v76, 10, v157
	s_waitcnt lgkmcnt(0)
	v_mfma_f32_16x16x32_bf16 v[52:55], v[144:147], v[18:21], v[14:17]
	v_mov_b32_e32 v77, v69
	v_lshlrev_b32_e32 v68, 1, v154
	v_lshl_add_u64 v[76:77], v[152:153], 0, v[76:77]
	v_lshl_add_u64 v[16:17], v[12:13], 0, s[16:17]
	global_load_lds_dwordx4 v[16:17], off
	ds_read_b128 v[12:15], v1 offset:4096
	v_mfma_f32_16x16x32_bf16 v[28:31], v[40:43], v[28:31], 0
	s_waitcnt vmcnt(0)
	v_sub_u32_e32 v100, 0, v68
	s_mov_b64 s[0:1], 0
	v_mfma_f32_16x16x32_bf16 v[136:139], v[40:43], v[56:59], 0
	s_waitcnt lgkmcnt(0)
	s_add_i32 s66, s66, 4
	s_mov_b64 s[68:69], exec
	s_mov_b64 exec, 1
	s_nop 1
	ds_add_u32 v168, v169
	s_movk_i32 s67, 0x800

; #define MFMA16(a, b, c) __builtin_amdgcn_mfma_f32_16x16x32_bf16((a), (b), (c), 0, 0, 0)
; #define LAS __attribute__((address_space(3)))
; template <class FA, class FB, class FL, class FS>
; DI void gemm_tile(char* lds, int ksteps, int rot, FA fa, FB fb, FL fl, FS fs) {
;     ...
;   for (int ks = 0; ks < ksteps; ++ks) {
;     const int cur = ks & 1;
;     if (ks + 1 < ksteps) {
;       int kn = ks + 1 + rot; if (kn >= ksteps) kn -= ksteps;
;       LAS char* dst = l3 + (cur ^ 1) * 32768;
; #pragma unroll
;       for (int i = 0; i < 4; ++i) {
;         const int id = tid + i * 256, r = id >> 3, c = (id & 7) ^ (r & 7);
;         __builtin_amdgcn_global_load_lds((const unsigned*)fa(r, kn * 8 + c), (LAS unsigned*)(dst + id * 16), 16, 0, 0);
;         __builtin_amdgcn_global_load_lds((const unsigned*)fb(r, kn * 8 + c), (LAS unsigned*)(dst + 16384 + id * 16), 16, 0, 0);
;       }
;     }
;     const char* A = lds + cur * 32768;
;     const char* B = A + 16384;
; #pragma unroll
;     for (int kk = 0; kk < 2; ++kk) {
;       bf16x8 af[4], bq[4];
; #pragma unroll
;       for (int m = 0; m < 4; ++m) af[m] = ldfrag(A, 128, wr * 64 + m * 16 + fr, kk * 4 + fq);
; #pragma unroll
;       for (int n = 0; n < 4; ++n) bq[n] = ldfrag(B, 128, wc * 64 + n * 16 + fr, kk * 4 + fq);
; #pragma unroll
;       for (int m = 0; m < 4; ++m)
; #pragma unroll
;         for (int n = 0; n < 4; ++n) acc[m][n] = MFMA16(bq[n], af[m], acc[m][n]);
;     }
;     asm volatile("s_waitcnt vmcnt(0)" ::: "memory");
;     __syncthreads();
.Ls5sb_done1:
	s_mov_b64 exec, s[68:69]
	s_nop 1
	v_mfma_f32_16x16x32_bf16 v[64:67], v[124:127], v[18:21], v[36:39]
	v_mfma_f32_16x16x32_bf16 v[60:63], v[132:135], v[18:21], v[44:47]
	v_mfma_f32_16x16x32_bf16 v[56:59], v[140:143], v[18:21], v[48:51]
	v_mfma_f32_16x16x32_bf16 v[48:51], v[124:127], v[32:35], v[72:75]
	v_mfma_f32_16x16x32_bf16 v[44:47], v[132:135], v[32:35], v[92:95]
	s_nop 1
	v_lshlrev_b32_e32 v72, 10, v155
	v_mov_b32_e32 v73, v69
	v_lshlrev_b32_e32 v74, 10, v156
	v_mfma_f32_16x16x32_bf16 v[40:43], v[140:143], v[32:35], v[96:99]
	v_lshrrev_b32_e32 v92, 4, v0
	v_lshrrev_b32_e32 v93, 4, v2
	v_lshrrev_b32_e32 v94, 4, v4
	v_mfma_f32_16x16x32_bf16 v[36:39], v[144:147], v[32:35], v[28:31]
	v_lshrrev_b32_e32 v95, 4, v6
	v_mov_b32_e32 v75, v69
	v_lshl_add_u64 v[72:73], v[152:153], 0, v[72:73]
	v_mfma_f32_16x16x32_bf16 v[32:35], v[124:127], v[12:15], v[104:107]
	v_lshl_add_u64 v[74:75], v[152:153], 0, v[74:75]
	v_lshlrev_b32_e32 v96, 3, v158
	v_lshlrev_b32_e32 v97, 3, v159
	v_mfma_f32_16x16x32_bf16 v[28:31], v[132:135], v[12:15], v[108:111]
	v_lshlrev_b32_e32 v98, 3, v160
	v_lshlrev_b32_e32 v99, 3, v161
	v_mfma_f32_16x16x32_bf16 v[20:23], v[140:143], v[12:15], v[112:115]
	v_mfma_f32_16x16x32_bf16 v[16:19], v[144:147], v[12:15], v[116:119]
	v_mfma_f32_16x16x32_bf16 v[12:15], v[124:127], v[148:151], v[8:11]
	v_mfma_f32_16x16x32_bf16 v[8:11], v[132:135], v[148:151], v[120:123]
	v_mfma_f32_16x16x32_bf16 v[4:7], v[140:143], v[148:151], v[128:131]
	v_mfma_f32_16x16x32_bf16 v[0:3], v[144:147], v[148:151], v[136:139]
	s_branch .LBB0_627
.LBB0_626:
	s_or_b64 exec, exec, s[2:3]
	v_add_u32_e32 v68, s40, v102
	v_add_u32_e32 v101, v68, v87
	v_add_u32_e32 v124, v101, v88
	ds_read_b128 v[104:107], v124 offset:16384
	v_add_u32_e32 v101, v101, v89
	ds_read_b128 v[108:111], v124 offset:18432
	ds_read_b128 v[112:115], v101
	ds_read_b128 v[116:119], v101 offset:2048
	ds_read_b128 v[120:123], v124 offset:20480
	ds_read_b128 v[124:127], v124 offset:22528
	s_waitcnt lgkmcnt(0)
	v_mfma_f32_16x16x32_bf16 v[60:63], v[108:111], v[112:115], v[60:63]
	v_add_u32_e32 v68, v68, v90
	s_add_i32 s37, s37, 1
	s_add_i32 s39, s39, 0x8000
	v_mfma_f32_16x16x32_bf16 v[64:67], v[104:107], v[112:115], v[64:67]
	s_add_i32 s38, s38, 64
	v_cmp_eq_u32_e32 vcc, s37, v100
	s_or_b64 s[0:1], vcc, s[0:1]
	v_mfma_f32_16x16x32_bf16 v[56:59], v[120:123], v[112:115], v[56:59]
	v_mfma_f32_16x16x32_bf16 v[52:55], v[124:127], v[112:115], v[52:55]
	v_mfma_f32_16x16x32_bf16 v[48:51], v[104:107], v[116:119], v[48:51]
	v_mfma_f32_16x16x32_bf16 v[44:47], v[108:111], v[116:119], v[44:47]
	v_mfma_f32_16x16x32_bf16 v[40:43], v[120:123], v[116:119], v[40:43]
	v_mfma_f32_16x16x32_bf16 v[36:39], v[124:127], v[116:119], v[36:39]
	ds_read_b128 v[112:115], v101 offset:4096
	ds_read_b128 v[116:119], v101 offset:6144
	v_add_u32_e32 v101, v68, v88
	v_add_u32_e32 v68, v68, v89
	s_waitcnt lgkmcnt(1)
	v_mfma_f32_16x16x32_bf16 v[32:35], v[104:107], v[112:115], v[32:35]
	v_mfma_f32_16x16x32_bf16 v[28:31], v[108:111], v[112:115], v[28:31]
	v_mfma_f32_16x16x32_bf16 v[20:23], v[120:123], v[112:115], v[20:23]
	v_mfma_f32_16x16x32_bf16 v[16:19], v[124:127], v[112:115], v[16:19]
	s_waitcnt lgkmcnt(0)
	v_mfma_f32_16x16x32_bf16 v[12:15], v[104:107], v[116:119], v[12:15]
	ds_read_b128 v[104:107], v101 offset:16384
	v_mfma_f32_16x16x32_bf16 v[8:11], v[108:111], v[116:119], v[8:11]
	v_mfma_f32_16x16x32_bf16 v[4:7], v[120:123], v[116:119], v[4:7]
	v_mfma_f32_16x16x32_bf16 v[0:3], v[124:127], v[116:119], v[0:3]
	ds_read_b128 v[108:111], v101 offset:18432
	ds_read_b128 v[112:115], v68
	ds_read_b128 v[116:119], v68 offset:2048
	ds_read_b128 v[120:123], v101 offset:20480
	ds_read_b128 v[124:127], v101 offset:22528
	s_waitcnt lgkmcnt(3)
	v_mfma_f32_16x16x32_bf16 v[64:67], v[104:107], v[112:115], v[64:67]
	v_mfma_f32_16x16x32_bf16 v[60:63], v[108:111], v[112:115], v[60:63]
	s_waitcnt lgkmcnt(1)
	v_mfma_f32_16x16x32_bf16 v[56:59], v[120:123], v[112:115], v[56:59]
	s_waitcnt lgkmcnt(0)
	v_mfma_f32_16x16x32_bf16 v[52:55], v[124:127], v[112:115], v[52:55]
	v_mfma_f32_16x16x32_bf16 v[48:51], v[104:107], v[116:119], v[48:51]
	v_mfma_f32_16x16x32_bf16 v[44:47], v[108:111], v[116:119], v[44:47]
	v_mfma_f32_16x16x32_bf16 v[40:43], v[120:123], v[116:119], v[40:43]
	v_mfma_f32_16x16x32_bf16 v[36:39], v[124:127], v[116:119], v[36:39]
	ds_read_b128 v[112:115], v68 offset:4096
	ds_read_b128 v[116:119], v68 offset:6144
	s_waitcnt vmcnt(0)
	s_waitcnt lgkmcnt(0)
	v_mfma_f32_16x16x32_bf16 v[32:35], v[104:107], v[112:115], v[32:35]
	s_add_i32 s66, s66, 4
	s_mov_b64 s[68:69], exec
	s_mov_b64 exec, 1
	s_nop 1
	ds_add_u32 v168, v169
	s_movk_i32 s67, 0x800

; #define MFMA16(a, b, c) __builtin_amdgcn_mfma_f32_16x16x32_bf16((a), (b), (c), 0, 0, 0)
; template <class FA, class FB, class FL, class FS>
; DI void gemm_tile(char* lds, int ksteps, int rot, FA fa, FB fb, FL fl, FS fs) {
;     ...
;       for (int m = 0; m < 4; ++m)
; #pragma unroll
;         for (int n = 0; n < 4; ++n) acc[m][n] = MFMA16(bq[n], af[m], acc[m][n]);
;     }
;     asm volatile("s_waitcnt vmcnt(0)" ::: "memory");
;     __syncthreads();
;   }
.Ls5sb_done2:
	s_mov_b64 exec, s[68:69]
	s_nop 1
	v_mfma_f32_16x16x32_bf16 v[28:31], v[108:111], v[112:115], v[28:31]
	v_mfma_f32_16x16x32_bf16 v[20:23], v[120:123], v[112:115], v[20:23]
	v_mfma_f32_16x16x32_bf16 v[16:19], v[124:127], v[112:115], v[16:19]
	v_mfma_f32_16x16x32_bf16 v[12:15], v[104:107], v[116:119], v[12:15]
	v_mfma_f32_16x16x32_bf16 v[8:11], v[108:111], v[116:119], v[8:11]
	v_mfma_f32_16x16x32_bf16 v[4:7], v[120:123], v[116:119], v[4:7]
	v_mfma_f32_16x16x32_bf16 v[0:3], v[124:127], v[116:119], v[0:3]
	s_andn2_b64 exec, exec, s[0:1]
	s_cbranch_execz .LBB0_624
